# v40 + token pass: second-stage row load and LIN row load issued at the row top into spare registers (were issued and waited mid-row)
# baseline (speedup 1.0000x reference)
; __device__ __forceinline__ float bflo(unsigned w) { return __uint_as_float(w << 16); }
; __device__ __forceinline__ float bfhi(unsigned w) { return __uint_as_float(w & 0xffff0000u); }
; __device__ __forceinline__ unsigned pkbf(float lo, float hi) { return pg8::cvt_pk_bf16(lo, hi); }
; __device__ __forceinline__ void p5_row(const P& p, int row, int lane) {
;     unsigned char* ws = p.ws;
;     bf16_t* za = (bf16_t*)(ws + WS_ZA) + (size_t)row * 768;
;     { unsigned* q = (unsigned*)(za + lane * 6); const unsigned w0 = q[0], w1 = q[1], w2 = q[2];
;       float f[6] = {bflo(w0), bfhi(w0), bflo(w1), bfhi(w1), bflo(w2), bfhi(w2)}; float s = 0.f;
; #pragma unroll
;       for (int e = 0; e < 6; ++e) s += f[e] * f[e];
;       const float rstd = 1.0f / sqrtf(wave_sum(s) * (1.f / 384.f) + NORM_EPS); const float* g = p.in[8] + lane * 6;
; #pragma unroll
;       for (int e = 0; e < 6; ++e) f[e] = f[e] * rstd * g[e];
;       q[0] = pkbf(f[0], f[1]); q[1] = pkbf(f[2], f[3]); q[2] = pkbf(f[4], f[5]); }
;     { unsigned* q = (unsigned*)(za + 384 + lane * 4); const unsigned w0 = q[0], w1 = q[1];
;       float f[4] = {bflo(w0), bfhi(w0), bflo(w1), bfhi(w1)}; float s = 0.f;
; #pragma unroll
;       for (int e = 0; e < 4; ++e) s += f[e] * f[e];
;       const float rstd = 1.0f / sqrtf(wave_sum(s) * (1.f / 256.f) + NORM_EPS); const float* g = p.in[10] + lane * 4;
; #pragma unroll
;       for (int e = 0; e < 4; ++e) f[e] = f[e] * rstd * g[e];
;       q[0] = pkbf(f[0], f[1]); q[1] = pkbf(f[2], f[3]); }
.LBB0_419:
	v_lshl_add_u64 v[0:1], s[50:51], 0, v[26:27]
	v_add_co_u32_e32 v4, vcc, 0x12000000, v0
	s_nop 1
	v_addc_co_u32_e32 v5, vcc, 0, v1, vcc
	global_load_dwordx3 v[0:2], v[4:5], off
	v_lshl_add_u64 v[218:219], s[50:51], 0, v[24:25]
	s_mov_b64 s[98:99], 0x12000000
	v_lshl_add_u64 v[218:219], v[218:219], 0, s[98:99]
	global_load_dwordx2 v[220:221], v[218:219], off offset:768
	v_lshl_add_u64 v[216:217], s[50:51], 0, v[22:23]
	s_mov_b64 s[100:101], 0x16800000
	v_lshl_add_u64 v[216:217], v[216:217], 0, s[100:101]
	global_load_dwordx3 v[222:224], v[216:217], off
	s_waitcnt vmcnt(0)
	v_lshlrev_b32_e32 v6, 16, v0
	v_and_b32_e32 v10, 0xffff0000, v0
	v_lshlrev_b32_e32 v34, 16, v1
	v_and_b32_e32 v35, 0xffff0000, v1
	global_load_dwordx4 v[42:45], v[12:13], off
	global_load_dwordx2 v[0:1], v[12:13], off offset:16
	v_mul_f32_e32 v8, v10, v10
	v_fmac_f32_e32 v8, v6, v6
	v_fmac_f32_e32 v8, v34, v34
	v_lshlrev_b32_e32 v41, 16, v2
	v_fmac_f32_e32 v8, v35, v35
	v_and_b32_e32 v2, 0xffff0000, v2
	v_fmac_f32_e32 v8, v41, v41
	v_fmac_f32_e32 v8, v2, v2
	s_nop 1
	v_add_f32_dpp v8, v8, v8 quad_perm:[1,0,3,2] row_mask:0xf bank_mask:0xf bound_ctrl:1
	s_nop 1
	v_add_f32_dpp v8, v8, v8 quad_perm:[2,3,0,1] row_mask:0xf bank_mask:0xf bound_ctrl:1
	s_nop 1
	v_add_f32_dpp v8, v8, v8 row_half_mirror row_mask:0xf bank_mask:0xf bound_ctrl:1
	s_nop 1
	v_add_f32_dpp v8, v8, v8 row_mirror row_mask:0xf bank_mask:0xf bound_ctrl:1
	s_nop 0
	v_readlane_b32 s98, v8, 0
	v_readlane_b32 s99, v8, 16
	v_readlane_b32 s100, v8, 32
	v_readlane_b32 s101, v8, 48
	v_mov_b32_e32 v8, s98
	v_add_f32_e32 v8, s99, v8
	v_mov_b32_e32 v9, s100
	v_add_f32_e32 v9, s101, v9
	v_add_f32_e32 v8, v8, v9
	v_fmamk_f32 v8, v8, 0x3b2aaaab, v39
	v_mul_f32_e32 v9, 0x4f800000, v8
	v_cmp_gt_f32_e32 vcc, s24, v8
	s_nop 1
	v_cndmask_b32_e32 v46, v8, v9, vcc
	v_sqrt_f32_e32 v47, v46
	v_lshl_add_u64 v[8:9], s[50:51], 0, v[24:25]
	v_add_u32_e32 v48, -1, v47
	v_add_u32_e32 v49, 1, v47
	v_fma_f32 v50, -v48, v47, v46
	v_fma_f32 v51, -v49, v47, v46
	v_cmp_ge_f32_e64 s[0:1], 0, v50
	s_nop 1
	v_cndmask_b32_e64 v47, v47, v48, s[0:1]
	v_cmp_lt_f32_e64 s[0:1], 0, v51
	s_nop 1
	v_cndmask_b32_e64 v47, v47, v49, s[0:1]
	v_mul_f32_e32 v48, 0x37800000, v47
	v_cndmask_b32_e32 v47, v47, v48, vcc
	v_cmp_class_f32_e32 vcc, v46, v40
	s_nop 1
	v_cndmask_b32_e32 v46, v47, v46, vcc
	v_div_scale_f32 v47, s[0:1], v46, v46, 1.0
	v_rcp_f32_e32 v48, v47
	v_add_co_u32_e32 v8, vcc, s3, v8
	v_fma_f32 v50, -v47, v48, 1.0
	s_nop 0
	v_addc_co_u32_e32 v9, vcc, 0, v9, vcc
	v_div_scale_f32 v49, vcc, 1.0, v46, 1.0
	v_fmac_f32_e32 v48, v50, v48
	v_mul_f32_e32 v50, v49, v48
	v_fma_f32 v51, -v47, v50, v49
	v_fmac_f32_e32 v50, v51, v48
	v_fma_f32 v47, -v47, v50, v49
	v_div_fmas_f32 v47, v47, v48, v50
	v_div_fixup_f32 v46, v47, v46, 1.0
	v_mul_f32_e32 v6, v46, v6
	v_mul_f32_e32 v10, v46, v10
	v_mul_f32_e32 v41, v46, v41
	v_mul_f32_e32 v2, v46, v2
	v_mul_f32_e32 v34, v46, v34
	v_mul_f32_e32 v35, v46, v35
	s_waitcnt vmcnt(1)
	v_mul_f32_e32 v6, v42, v6
	v_mul_f32_e32 v10, v43, v10
	s_waitcnt vmcnt(0)
	v_mul_f32_e32 v0, v0, v41
	v_mul_f32_e32 v1, v1, v2
	v_cvt_pk_bf16_f32 v2, v6, v10
	v_mul_f32_e32 v34, v44, v34
	v_mul_f32_e32 v35, v45, v35
	global_store_dword v[4:5], v2, off
	v_cvt_pk_bf16_f32 v2, v34, v35
	global_store_dword v[4:5], v2, off offset:4
	v_cvt_pk_bf16_f32 v0, v0, v1
	global_store_dword v[4:5], v0, off offset:8
	v_mov_b64_e32 v[0:1], v[220:221]
	s_nop 0
	global_load_dwordx4 v[42:45], v[14:15], off
	s_waitcnt vmcnt(1)
	v_lshlrev_b32_e32 v2, 16, v0
	v_and_b32_e32 v0, 0xffff0000, v0
	v_mul_f32_e32 v5, v0, v0
	v_lshlrev_b32_e32 v4, 16, v1
	v_fmac_f32_e32 v5, v2, v2
	v_and_b32_e32 v1, 0xffff0000, v1
	v_fmac_f32_e32 v5, v4, v4
	v_fmac_f32_e32 v5, v1, v1
	s_nop 1
	v_add_f32_dpp v5, v5, v5 quad_perm:[1,0,3,2] row_mask:0xf bank_mask:0xf bound_ctrl:1
	s_nop 1
	v_add_f32_dpp v5, v5, v5 quad_perm:[2,3,0,1] row_mask:0xf bank_mask:0xf bound_ctrl:1
	s_nop 1
	v_add_f32_dpp v5, v5, v5 row_half_mirror row_mask:0xf bank_mask:0xf bound_ctrl:1
	s_nop 1
	v_add_f32_dpp v5, v5, v5 row_mirror row_mask:0xf bank_mask:0xf bound_ctrl:1
	s_nop 0
	v_readlane_b32 s98, v5, 0
	v_readlane_b32 s99, v5, 16
	v_readlane_b32 s100, v5, 32
	v_readlane_b32 s101, v5, 48
	v_mov_b32_e32 v5, s98
	v_add_f32_e32 v5, s99, v5
	v_mov_b32_e32 v6, s100
	v_add_f32_e32 v6, s101, v6
	v_add_f32_e32 v5, v5, v6
	v_fmamk_f32 v5, v5, 0x3b800000, v39
	v_mul_f32_e32 v6, 0x4f800000, v5
	v_cmp_gt_f32_e32 vcc, s24, v5
	s_nop 1
	v_cndmask_b32_e32 v5, v5, v6, vcc
	v_sqrt_f32_e32 v6, v5
	s_nop 0
	v_add_u32_e32 v10, -1, v6
	v_add_u32_e32 v34, 1, v6
	v_fma_f32 v35, -v10, v6, v5
	v_fma_f32 v41, -v34, v6, v5
	v_cmp_ge_f32_e64 s[0:1], 0, v35
	s_nop 1
	v_cndmask_b32_e64 v6, v6, v10, s[0:1]
	v_cmp_lt_f32_e64 s[0:1], 0, v41
	s_nop 1
	v_cndmask_b32_e64 v6, v6, v34, s[0:1]
	v_mul_f32_e32 v10, 0x37800000, v6
	v_cndmask_b32_e32 v6, v6, v10, vcc
	v_cmp_class_f32_e32 vcc, v5, v40
	s_nop 1
	v_cndmask_b32_e32 v5, v6, v5, vcc
	v_div_scale_f32 v6, s[0:1], v5, v5, 1.0
	v_rcp_f32_e32 v10, v6
	v_div_scale_f32 v34, vcc, 1.0, v5, 1.0
	v_fma_f32 v35, -v6, v10, 1.0
	v_fmac_f32_e32 v10, v35, v10
	v_mul_f32_e32 v35, v34, v10
	v_fma_f32 v41, -v6, v35, v34
	v_fmac_f32_e32 v35, v41, v10
	v_fma_f32 v6, -v6, v35, v34
	v_div_fmas_f32 v6, v6, v10, v35
	v_div_fixup_f32 v5, v6, v5, 1.0
	v_mul_f32_e32 v0, v5, v0
	v_mul_f32_e32 v2, v5, v2
	s_waitcnt vmcnt(0)
	v_mul_f32_e32 v0, v43, v0
	v_mul_f32_e32 v4, v5, v4
	v_mul_f32_e32 v1, v5, v1
	v_mul_f32_e32 v2, v42, v2
	v_cvt_pk_bf16_f32 v0, v2, v0
	v_mul_f32_e32 v4, v44, v4
	v_mul_f32_e32 v1, v45, v1
	global_store_dword v[8:9], v0, off offset:768
	v_cvt_pk_bf16_f32 v0, v4, v1
	global_store_dword v[8:9], v0, off offset:772
	s_and_saveexec_b64 s[0:1], s[4:5]
	s_xor_b64 s[0:1], exec, s[0:1]
	s_and_b32 s14, s26, 0x1fff
	s_add_i32 s15, s26, 0xffff8000
	s_or_saveexec_b64 s[0:1], s[0:1]
	v_mov_b32_e32 v4, s15
	v_mov_b32_e32 v5, s14
	s_xor_b64 exec, exec, s[0:1]
	s_cbranch_execz .LBB0_423
; __device__ __forceinline__ unsigned pkbf(float lo, float hi) { return pg8::cvt_pk_bf16(lo, hi); }
; __device__ __forceinline__ void p5_row(const P& p, int row, int lane) {
;     ...
;     if (lane < 16) { const float x1 = __uint_as_float((unsigned)za[640 + lane] << 16), x2 = __uint_as_float((unsigned)za[656 + lane] << 16);
;       const float* rp = (const float*)(ws + WS_ROPE) + ((size_t)seq_pos(row) * 16 + lane) * 2; const float c = rp[0], s = rp[1];
;       const unsigned w = pkbf(x1 * c - x2 * s, x1 * s + x2 * c);
;       unsigned* kr = (unsigned*)((bf16_t*)((unsigned char*)p.out + DO_K) + (size_t)row * 768 + 64) + lane;
; #pragma unroll
;       for (int h = 0; h < NH; ++h) kr[h * 48] = w; }
;     { const int pos = seq_pos(row), L = row < TP ? 8192 : 16384;
;       const bf16_t* zl = (const bf16_t*)(ws + WS_ZL) + (size_t)row * 512 + lane * 6;
;       const unsigned* q = (const unsigned*)zl; const unsigned w0 = q[0], w1 = q[1], w2 = q[2];
;       unsigned p0 = 0, p1 = 0, p2 = 0, n0 = 0, n1 = 0, n2 = 0;
;       if (pos > 0) { const unsigned* qq = (const unsigned*)(zl - 512); p0 = qq[0]; p1 = qq[1]; p2 = qq[2]; }
;       if (pos < L - 1) { const unsigned* qq = (const unsigned*)(zl + 512); n0 = qq[0]; n1 = qq[1]; n2 = qq[2]; }
	s_and_b32 s27, s26, 0x1fff
	s_add_i32 s28, s26, 0xffff8000
	v_lshl_add_u64 v[0:1], s[50:51], 0, v[28:29]
	s_cmp_lt_i32 s26, 0x8000
	v_add_co_u32_e32 v0, vcc, 0x12000000, v0
	s_cselect_b32 s18, s27, s28
	s_nop 0
	v_addc_co_u32_e32 v1, vcc, 0, v1, vcc
	s_lshl_b64 s[14:15], s[18:19], 7
	v_lshl_add_u64 v[4:5], v[16:17], 0, s[14:15]
	global_load_ushort v2, v[0:1], off offset:1280
	global_load_ushort v6, v[0:1], off offset:1312
	s_nop 0
	global_load_dwordx2 v[0:1], v[4:5], off
	v_mov_b32_e32 v4, s28
	s_waitcnt vmcnt(2)
	v_lshlrev_b32_e32 v2, 16, v2
	s_waitcnt vmcnt(1)
	v_lshlrev_b32_e32 v5, 16, v6
	s_waitcnt vmcnt(0)
	v_mul_f32_e32 v6, v1, v5
	v_mul_f32_e32 v5, v0, v5
	v_fma_f32 v0, v0, v2, -v6
	v_fmac_f32_e32 v5, v1, v2
	v_cvt_pk_bf16_f32 v0, v0, v5
	v_mov_b32_e32 v5, s27
	global_store_dword v[30:31], v0, off
	global_store_dword v[30:31], v0, off offset:192
	global_store_dword v[30:31], v0, off offset:384
	global_store_dword v[30:31], v0, off offset:576
	global_store_dword v[30:31], v0, off offset:768
	global_store_dword v[30:31], v0, off offset:960
	global_store_dword v[30:31], v0, off offset:1152
	global_store_dword v[30:31], v0, off offset:1344
.LBB0_423:
	s_or_b64 exec, exec, s[0:1]
	v_lshl_add_u64 v[34:35], s[50:51], 0, v[22:23]
	v_add_co_u32_e32 v0, vcc, 0x16800000, v34
	s_cmp_lt_i32 s26, 0x8000
	s_nop 0
	v_addc_co_u32_e32 v1, vcc, 0, v35, vcc
	v_mov_b32_e32 v0, v222
	v_mov_b32_e32 v1, v223
	v_mov_b32_e32 v2, v224
	s_cselect_b64 s[0:1], -1, 0
	v_cndmask_b32_e64 v4, v4, v5, s[0:1]
	v_mov_b32_e32 v6, 0
	v_cmp_ne_u32_e32 vcc, 0, v4
	v_mov_b32_e32 v8, 0
	v_mov_b32_e32 v9, 0
	v_mov_b32_e32 v10, 0
	s_and_saveexec_b64 s[14:15], vcc
	s_cbranch_execz .LBB0_425
	v_add_co_u32_e32 v8, vcc, 0x167ff000, v34
	s_nop 1
	v_addc_co_u32_e32 v9, vcc, 0, v35, vcc
	global_load_dwordx3 v[8:10], v[8:9], off offset:3072
